# prep filter tasks: w_filt2 rows and bias requested together with w_filt1 (one round trip instead of five)
# baseline (speedup 1.0000x reference)
.LBB0_1238:
	s_or_b64 exec, exec, s[16:17]
	v_lshl_or_b32 v4, v2, 6, v34
	v_ashrrev_i32_e32 v5, 31, v4
	v_lshlrev_b64 v[18:19], 2, v[4:5]
	v_lshl_add_u64 v[4:5], s[62:63], 0, v[18:19]
	s_waitcnt lgkmcnt(0)
	s_barrier
	global_load_dword v0, v[4:5], off
	s_movk_i32 s3, 0x2100
	v_mad_i64_i32 v[4:5], s[12:13], v2, s3, v[38:39]
	v_add_co_u32_e32 v6, vcc, s37, v4
	s_mov_b64 s[16:17], 0
	s_nop 0
	v_addc_co_u32_e32 v7, vcc, 0, v5, vcc
	v_add_co_u32_e32 v8, vcc, s85, v4
	global_load_dword v46, v[6:7], off offset:1792
	global_load_dword v47, v[6:7], off offset:2048
	v_addc_co_u32_e32 v9, vcc, 0, v5, vcc
	global_load_dword v48, v[6:7], off offset:2304
	global_load_dword v49, v[6:7], off offset:2560
	global_load_dword v50, v[6:7], off offset:2816
	global_load_dword v51, v[6:7], off offset:3072
	global_load_dword v52, v[6:7], off offset:3328
	global_load_dword v53, v[6:7], off offset:3584
	global_load_dword v66, v[6:7], off offset:3840
	global_load_dword v67, v[8:9], off
	global_load_dword v3, v[4:5], off
	global_load_dword v33, v[4:5], off offset:256
	global_load_dword v78, v[4:5], off offset:512
	global_load_dword v79, v[4:5], off offset:768
	global_load_dword v80, v[4:5], off offset:1024
	global_load_dword v81, v[4:5], off offset:1280
	global_load_dword v82, v[4:5], off offset:1536
	global_load_dword v83, v[4:5], off offset:1792
	global_load_dword v84, v[4:5], off offset:2048
	global_load_dword v85, v[4:5], off offset:2304
	global_load_dword v86, v[4:5], off offset:2560
	global_load_dword v87, v[4:5], off offset:2816
	global_load_dword v88, v[4:5], off offset:3072
	global_load_dword v89, v[4:5], off offset:3328
	global_load_dword v90, v[4:5], off offset:3584
	global_load_dword v91, v[4:5], off offset:3840
	global_load_dword v92, v[8:9], off offset:-4096
	global_load_dword v93, v[6:7], off offset:256
	global_load_dword v94, v[6:7], off offset:512
	global_load_dword v95, v[6:7], off offset:768
	global_load_dword v96, v[6:7], off offset:1024
	global_load_dword v97, v[6:7], off offset:1280
	global_load_dword v98, v[6:7], off offset:1536
	v_lshl_add_u64 v[4:5], s[64:65], 0, v[18:19]
	global_load_dword v99, v[4:5], off
	v_lshl_add_u64 v[186:187], s[80:81], 0, v[18:19]
	v_mov_b32_e32 v188, v2
	v_ashrrev_i32_e32 v189, 31, v2
	global_load_dword v181, v[186:187], off
	v_lshlrev_b64 v[188:189], 14, v[188:189]
	s_nop 0
	v_lshl_add_u64 v[188:189], v[40:41], 0, v[188:189]
	s_nop 0
	global_load_dword v112, v[188:189], off offset:0
	global_load_dword v113, v[188:189], off offset:256
	global_load_dword v114, v[188:189], off offset:512
	global_load_dword v115, v[188:189], off offset:768
	global_load_dword v116, v[188:189], off offset:1024
	global_load_dword v117, v[188:189], off offset:1280
	global_load_dword v118, v[188:189], off offset:1536
	global_load_dword v119, v[188:189], off offset:1792
	global_load_dword v120, v[188:189], off offset:2048
	global_load_dword v121, v[188:189], off offset:2304
	global_load_dword v122, v[188:189], off offset:2560
	global_load_dword v123, v[188:189], off offset:2816
	global_load_dword v124, v[188:189], off offset:3072
	global_load_dword v125, v[188:189], off offset:3328
	global_load_dword v126, v[188:189], off offset:3584
	global_load_dword v127, v[188:189], off offset:3840
	v_add_co_u32_e32 v188, vcc, 0x1000, v188
	s_nop 1
	v_addc_co_u32_e32 v189, vcc, 0, v189, vcc
	s_nop 0
	global_load_dword v128, v[188:189], off offset:0
	global_load_dword v129, v[188:189], off offset:256
	global_load_dword v130, v[188:189], off offset:512
	global_load_dword v131, v[188:189], off offset:768
	global_load_dword v132, v[188:189], off offset:1024
	global_load_dword v133, v[188:189], off offset:1280
	global_load_dword v134, v[188:189], off offset:1536
	global_load_dword v135, v[188:189], off offset:1792
	global_load_dword v136, v[188:189], off offset:2048
	global_load_dword v137, v[188:189], off offset:2304
	global_load_dword v138, v[188:189], off offset:2560
	global_load_dword v139, v[188:189], off offset:2816
	global_load_dword v140, v[188:189], off offset:3072
	global_load_dword v141, v[188:189], off offset:3328
	global_load_dword v142, v[188:189], off offset:3584
	global_load_dword v143, v[188:189], off offset:3840
	v_add_co_u32_e32 v188, vcc, 0x1000, v188
	s_nop 1
	v_addc_co_u32_e32 v189, vcc, 0, v189, vcc
	s_nop 0
	global_load_dword v144, v[188:189], off offset:0
	global_load_dword v145, v[188:189], off offset:256
	global_load_dword v146, v[188:189], off offset:512
	global_load_dword v147, v[188:189], off offset:768
	global_load_dword v148, v[188:189], off offset:1024
	global_load_dword v149, v[188:189], off offset:1280
	global_load_dword v150, v[188:189], off offset:1536
	global_load_dword v151, v[188:189], off offset:1792
	global_load_dword v152, v[188:189], off offset:2048
	global_load_dword v153, v[188:189], off offset:2304
	global_load_dword v154, v[188:189], off offset:2560
	global_load_dword v155, v[188:189], off offset:2816
	global_load_dword v156, v[188:189], off offset:3072
	global_load_dword v157, v[188:189], off offset:3328
	global_load_dword v158, v[188:189], off offset:3584
	global_load_dword v159, v[188:189], off offset:3840
	v_add_co_u32_e32 v188, vcc, 0x1000, v188
	s_nop 1
	v_addc_co_u32_e32 v189, vcc, 0, v189, vcc
	s_nop 0
	global_load_dword v160, v[188:189], off offset:0
	global_load_dword v161, v[188:189], off offset:256
	global_load_dword v162, v[188:189], off offset:512
	global_load_dword v163, v[188:189], off offset:768
	global_load_dword v164, v[188:189], off offset:1024
	global_load_dword v165, v[188:189], off offset:1280
	global_load_dword v166, v[188:189], off offset:1536
	global_load_dword v167, v[188:189], off offset:1792
	global_load_dword v168, v[188:189], off offset:2048
	global_load_dword v169, v[188:189], off offset:2304
	global_load_dword v175, v[188:189], off offset:2560
	global_load_dword v176, v[188:189], off offset:2816
	global_load_dword v177, v[188:189], off offset:3072
	global_load_dword v178, v[188:189], off offset:3328
	global_load_dword v179, v[188:189], off offset:3584
	global_load_dword v180, v[188:189], off offset:3840
	ds_read_b128 v[6:9], v65
	ds_read_b128 v[10:13], v65 offset:16
	ds_read2_b32 v[68:69], v65 offset0:23 offset1:24
	ds_read2_b32 v[70:71], v65 offset0:25 offset1:26
	ds_read2_b32 v[72:73], v65 offset0:27 offset1:28
	ds_read2_b32 v[74:75], v65 offset0:29 offset1:30
	ds_read_b128 v[14:17], v65 offset:32
	ds_read_b128 v[22:25], v65 offset:48
	ds_read2_b32 v[76:77], v65 offset0:31 offset1:32
	ds_read_b128 v[26:29], v65 offset:64
	ds_read_b96 v[30:32], v65 offset:80
	s_waitcnt vmcnt(30) lgkmcnt(7)
	v_pk_mul_f32 v[48:49], v[70:71], v[48:49]
	s_waitcnt vmcnt(28) lgkmcnt(6)
	v_pk_mul_f32 v[50:51], v[72:73], v[50:51]
	s_waitcnt vmcnt(26) lgkmcnt(5)
	v_pk_mul_f32 v[52:53], v[74:75], v[52:53]
	s_waitcnt vmcnt(24) lgkmcnt(2)
	v_pk_mul_f32 v[66:67], v[76:77], v[66:67]
	s_waitcnt vmcnt(23)
	v_fmac_f32_e32 v0, v6, v3
	s_waitcnt vmcnt(22)
	v_fmac_f32_e32 v0, v7, v33
	s_waitcnt vmcnt(21)
	v_fmac_f32_e32 v0, v8, v78
	s_waitcnt vmcnt(20)
	v_fmac_f32_e32 v0, v9, v79
	s_waitcnt vmcnt(19)
	v_fmac_f32_e32 v0, v10, v80
	s_waitcnt vmcnt(18)
	v_fmac_f32_e32 v0, v11, v81
	s_waitcnt vmcnt(17)
	v_fmac_f32_e32 v0, v12, v82
	s_waitcnt vmcnt(16)
	v_fmac_f32_e32 v0, v13, v83
	s_waitcnt vmcnt(15)
	v_fmac_f32_e32 v0, v14, v84
	s_waitcnt vmcnt(14)
	v_fmac_f32_e32 v0, v15, v85
	s_waitcnt vmcnt(13)
	v_fmac_f32_e32 v0, v16, v86
	s_waitcnt vmcnt(12)
	v_fmac_f32_e32 v0, v17, v87
	s_waitcnt vmcnt(11)
	v_fmac_f32_e32 v0, v22, v88
	s_waitcnt vmcnt(10)
	v_fmac_f32_e32 v0, v23, v89
	s_waitcnt vmcnt(9)
	v_fmac_f32_e32 v0, v24, v90
	s_waitcnt vmcnt(8)
	v_fmac_f32_e32 v0, v25, v91
	s_waitcnt vmcnt(7) lgkmcnt(1)
	v_fmac_f32_e32 v0, v26, v92
	s_waitcnt vmcnt(6)
	v_fmac_f32_e32 v0, v27, v93
	s_waitcnt vmcnt(5)
	v_fmac_f32_e32 v0, v28, v94
	s_waitcnt vmcnt(4)
	v_fmac_f32_e32 v0, v29, v95
	s_waitcnt vmcnt(3) lgkmcnt(0)
	v_fmac_f32_e32 v0, v30, v96
	s_waitcnt vmcnt(2)
	v_fmac_f32_e32 v0, v31, v97
	v_pk_mul_f32 v[46:47], v[68:69], v[46:47]
	s_waitcnt vmcnt(1)
	v_fmac_f32_e32 v0, v32, v98
	v_add_f32_e32 v0, v0, v46
	v_add_f32_e32 v0, v0, v47
	v_add_f32_e32 v0, v0, v48
	v_add_f32_e32 v0, v0, v49
	v_add_f32_e32 v0, v0, v50
	v_add_f32_e32 v0, v0, v51
	v_add_f32_e32 v0, v0, v52
	v_add_f32_e32 v0, v0, v53
	v_add_f32_e32 v0, v0, v66
	v_add_f32_e32 v0, v0, v67
	s_waitcnt vmcnt(0)
	v_mul_f32_e32 v0, v0, v99
	v_mul_f32_e32 v0, 0.15915494, v0
	v_sin_f32_e32 v0, v0
	v_lshl_add_u64 v[6:7], s[80:81], 0, v[18:19]
	v_ashrrev_i32_e32 v3, 31, v2
	v_mov_b32_e32 v8, v63
	ds_write_b32 v60, v0 offset:1280
	s_waitcnt lgkmcnt(0)
	s_barrier
	s_waitcnt vmcnt(0)
	v_mov_b32_e32 v0, v181
	ds_read_b128 v[10:13], v63 offset:0
	ds_read_b128 v[14:17], v63 offset:16
	ds_read_b128 v[22:25], v63 offset:32
	ds_read_b128 v[26:29], v63 offset:48
	s_waitcnt lgkmcnt(0)
	v_fmac_f32_e32 v0, v10, v112
	v_fmac_f32_e32 v0, v11, v113
	v_fmac_f32_e32 v0, v12, v114
	v_fmac_f32_e32 v0, v13, v115
	v_fmac_f32_e32 v0, v14, v116
	v_fmac_f32_e32 v0, v15, v117
	v_fmac_f32_e32 v0, v16, v118
	v_fmac_f32_e32 v0, v17, v119
	v_fmac_f32_e32 v0, v22, v120
	v_fmac_f32_e32 v0, v23, v121
	v_fmac_f32_e32 v0, v24, v122
	v_fmac_f32_e32 v0, v25, v123
	v_fmac_f32_e32 v0, v26, v124
	v_fmac_f32_e32 v0, v27, v125
	v_fmac_f32_e32 v0, v28, v126
	v_fmac_f32_e32 v0, v29, v127
	ds_read_b128 v[10:13], v63 offset:64
	ds_read_b128 v[14:17], v63 offset:80
	ds_read_b128 v[22:25], v63 offset:96
	ds_read_b128 v[26:29], v63 offset:112
	s_waitcnt lgkmcnt(0)
	v_fmac_f32_e32 v0, v10, v128
	v_fmac_f32_e32 v0, v11, v129
	v_fmac_f32_e32 v0, v12, v130
	v_fmac_f32_e32 v0, v13, v131
	v_fmac_f32_e32 v0, v14, v132
	v_fmac_f32_e32 v0, v15, v133
	v_fmac_f32_e32 v0, v16, v134
	v_fmac_f32_e32 v0, v17, v135
	v_fmac_f32_e32 v0, v22, v136
	v_fmac_f32_e32 v0, v23, v137
	v_fmac_f32_e32 v0, v24, v138
	v_fmac_f32_e32 v0, v25, v139
	v_fmac_f32_e32 v0, v26, v140
	v_fmac_f32_e32 v0, v27, v141
	v_fmac_f32_e32 v0, v28, v142
	v_fmac_f32_e32 v0, v29, v143
	ds_read_b128 v[10:13], v63 offset:128
	ds_read_b128 v[14:17], v63 offset:144
	ds_read_b128 v[22:25], v63 offset:160
	ds_read_b128 v[26:29], v63 offset:176
	s_waitcnt lgkmcnt(0)
	v_fmac_f32_e32 v0, v10, v144
	v_fmac_f32_e32 v0, v11, v145
	v_fmac_f32_e32 v0, v12, v146
	v_fmac_f32_e32 v0, v13, v147
	v_fmac_f32_e32 v0, v14, v148
	v_fmac_f32_e32 v0, v15, v149
	v_fmac_f32_e32 v0, v16, v150
	v_fmac_f32_e32 v0, v17, v151
	v_fmac_f32_e32 v0, v22, v152
	v_fmac_f32_e32 v0, v23, v153
	v_fmac_f32_e32 v0, v24, v154
	v_fmac_f32_e32 v0, v25, v155
	v_fmac_f32_e32 v0, v26, v156
	v_fmac_f32_e32 v0, v27, v157
	v_fmac_f32_e32 v0, v28, v158
	v_fmac_f32_e32 v0, v29, v159
	ds_read_b128 v[10:13], v63 offset:192
	ds_read_b128 v[14:17], v63 offset:208
	ds_read_b128 v[22:25], v63 offset:224
	ds_read_b128 v[26:29], v63 offset:240
	s_waitcnt lgkmcnt(0)
	v_fmac_f32_e32 v0, v10, v160
	v_fmac_f32_e32 v0, v11, v161
	v_fmac_f32_e32 v0, v12, v162
	v_fmac_f32_e32 v0, v13, v163
	v_fmac_f32_e32 v0, v14, v164
	v_fmac_f32_e32 v0, v15, v165
	v_fmac_f32_e32 v0, v16, v166
	v_fmac_f32_e32 v0, v17, v167
	v_fmac_f32_e32 v0, v22, v168
	v_fmac_f32_e32 v0, v23, v169
	v_fmac_f32_e32 v0, v24, v175
	v_fmac_f32_e32 v0, v25, v176
	v_fmac_f32_e32 v0, v26, v177
	v_fmac_f32_e32 v0, v27, v178
	v_fmac_f32_e32 v0, v28, v179
	v_fmac_f32_e32 v0, v29, v180
	v_mov_b32_e32 v5, v99
	v_lshlrev_b64 v[6:7], 18, v[2:3]
	v_mov_b32_e32 v8, 0
	v_lshl_add_u64 v[16:17], s[82:83], 0, v[6:7]
	v_lshl_add_u64 v[6:7], v[44:45], 0, v[6:7]
	s_mov_b32 s3, 0
	v_mov_b32_e32 v4, v64
	v_mov_b32_e32 v9, v8
	v_mov_b32_e32 v14, v8
	v_mov_b32_e32 v15, v8
	v_mov_b32_e32 v12, v8
	v_mov_b32_e32 v13, v8
	v_mov_b32_e32 v10, v8
	v_mov_b64_e32 v[18:19], v[6:7]
	v_mov_b32_e32 v11, v8
	s_waitcnt vmcnt(0)
	v_mul_f32_e32 v0, v0, v5
	v_mul_f32_e32 v0, 0.15915494, v0
	v_sin_f32_e32 v0, v0
	ds_write_b32 v60, v0 offset:3328
	s_waitcnt lgkmcnt(0)
	s_barrier
